# attn loop: second half of row-sum chain moved from QK gaps to PV gaps (VALU rebalance)
# speedup vs baseline: 1.0103x; 1.0001x over previous
.Lattn_h1:
	s_waitcnt lgkmcnt(3)
	v_mfma_f32_32x32x16_bf16 v[98:113], v[172:175], v[144:147], 0
	v_exp_f32_e32 v239, v66
	v_exp_f32_e32 v240, v67
	v_add_f32_e32 v202, 0, v229
	s_waitcnt lgkmcnt(2)
	v_mfma_f32_32x32x16_bf16 v[82:97], v[176:179], v[144:147], 0
	ds_read_b128 v[172:175], v219 offset:49152
	ds_read_b128 v[176:179], v219 offset:57344
	v_exp_f32_e32 v241, v68
	v_exp_f32_e32 v242, v69
	v_add_f32_e32 v202, v230, v202
	s_waitcnt lgkmcnt(3)
	v_mfma_f32_32x32x16_bf16 v[98:113], v[164:167], v[140:143], v[98:113]
	v_exp_f32_e32 v243, v70
	v_exp_f32_e32 v244, v71
	v_add_f32_e32 v202, v231, v202
	s_waitcnt lgkmcnt(2)
	v_mfma_f32_32x32x16_bf16 v[82:97], v[168:171], v[140:143], v[82:97]
	ds_read_b128 v[164:167], v216 offset:49152
	ds_read_b128 v[168:171], v216 offset:57344
	v_exp_f32_e32 v245, v72
	v_exp_f32_e32 v246, v73
	v_add_f32_e32 v202, v233, v202
	s_waitcnt lgkmcnt(3)
	v_mfma_f32_32x32x16_bf16 v[98:113], v[172:175], v[136:139], v[98:113]
	v_cvt_pk_bf16_f32 v66, v229, v230
	v_cvt_pk_bf16_f32 v67, v231, v233
	v_cvt_pk_bf16_f32 v68, v234, v236
	v_cvt_pk_bf16_f32 v69, v232, v235
	v_add_f32_e32 v202, v234, v202
	s_waitcnt lgkmcnt(2)
	v_mfma_f32_32x32x16_bf16 v[82:97], v[176:179], v[136:139], v[82:97]
	ds_read_b128 v[172:175], v215 offset:49152
	ds_read_b128 v[176:179], v215 offset:57344
	v_add_f32_e32 v202, v236, v202
	v_add_f32_e32 v202, v232, v202
	v_permlane32_swap_b32_e32 v66, v68
	v_permlane32_swap_b32_e32 v67, v69
	v_exp_f32_e32 v247, v74
	s_waitcnt lgkmcnt(3)
	v_mfma_f32_32x32x16_bf16 v[98:113], v[164:167], v[132:135], v[98:113]
	v_exp_f32_e32 v248, v75
	v_add_f32_e32 v202, v235, v202
	v_add_f32_e32 v202, v199, v202
	v_add_f32_e32 v202, v200, v202
	s_waitcnt lgkmcnt(2)
	v_mfma_f32_32x32x16_bf16 v[82:97], v[168:171], v[132:135], v[82:97]
	ds_read_b128 v[164:167], v214 offset:49152
	ds_read_b128 v[168:171], v214 offset:57344
	v_cvt_pk_bf16_f32 v70, v199, v200
	v_cvt_pk_bf16_f32 v71, v201, v227
	v_cvt_pk_bf16_f32 v72, v198, v225
	v_cvt_pk_bf16_f32 v73, v226, v228
	v_add_f32_e32 v202, v201, v202
	s_waitcnt lgkmcnt(3)
	v_mfma_f32_32x32x16_bf16 v[98:113], v[172:175], v[128:131], v[98:113]
	v_add_f32_e32 v202, v227, v202
	v_add_f32_e32 v202, v198, v202
	v_permlane32_swap_b32_e32 v70, v72
	v_permlane32_swap_b32_e32 v71, v73
	s_waitcnt vmcnt(0)
	ds_write_b128 v220, v[156:159] offset:32768
	ds_write_b128 v222, v[160:163] offset:32768
	s_waitcnt lgkmcnt(4)
	v_mfma_f32_32x32x16_bf16 v[82:97], v[176:179], v[128:131], v[82:97]
	ds_read_b128 v[172:175], v213 offset:49152
	ds_read_b128 v[176:179], v213 offset:57344
	v_exp_f32_e32 v249, v76
	v_exp_f32_e32 v250, v77
	v_add_f32_e32 v202, v225, v202
	s_waitcnt lgkmcnt(5)
	v_mfma_f32_32x32x16_bf16 v[98:113], v[164:167], v[124:127], v[98:113]
	v_exp_f32_e32 v251, v78
	v_exp_f32_e32 v252, v79
	v_add_f32_e32 v202, v226, v202
	s_waitcnt lgkmcnt(4)
	v_mfma_f32_32x32x16_bf16 v[82:97], v[168:171], v[124:127], v[82:97]
	ds_read_b128 v[164:167], v224 offset:49152
	ds_read_b128 v[168:171], v224 offset:57344
	v_exp_f32_e32 v182, v80
	v_exp_f32_e32 v183, v81
	v_add_f32_e32 v202, v228, v202
	s_waitcnt lgkmcnt(3)
	v_mfma_f32_32x32x16_bf16 v[98:113], v[172:175], v[120:123], v[98:113]
	v_cvt_pk_bf16_f32 v74, v239, v240
	v_cvt_pk_bf16_f32 v75, v241, v242
	v_cvt_pk_bf16_f32 v76, v243, v244
	v_cvt_pk_bf16_f32 v77, v245, v246
	s_waitcnt lgkmcnt(2)
	v_mfma_f32_32x32x16_bf16 v[82:97], v[176:179], v[120:123], v[82:97]
	v_cvt_pk_bf16_f32 v78, v247, v248
	v_cvt_pk_bf16_f32 v79, v249, v250
	v_permlane32_swap_b32_e32 v74, v76
	v_permlane32_swap_b32_e32 v75, v77
	ds_read_b64_tr_b16 v[198:199], v180 offset:0
	ds_read_b64_tr_b16 v[200:201], v180 offset:2048
	s_waitcnt lgkmcnt(3)
	v_mfma_f32_32x32x16_bf16 v[98:113], v[164:167], v[116:119], v[98:113]
	v_cvt_pk_bf16_f32 v80, v251, v252
	v_cvt_pk_bf16_f32 v81, v182, v183
	ds_read_b64_tr_b16 v[226:227], v180 offset:4096
	ds_read_b64_tr_b16 v[228:229], v180 offset:6144
	ds_read_b64_tr_b16 v[230:231], v180 offset:8192
	ds_read_b64_tr_b16 v[232:233], v180 offset:10240
	s_waitcnt lgkmcnt(6)
	v_mfma_f32_32x32x16_bf16 v[82:97], v[168:171], v[116:119], v[82:97]
	ds_read_b64_tr_b16 v[234:235], v180 offset:12288
	ds_read_b64_tr_b16 v[236:237], v180 offset:14336
	v_permlane32_swap_b32_e32 v78, v80
	v_permlane32_swap_b32_e32 v79, v81
	s_waitcnt lgkmcnt(6)
	v_mfma_f32_32x32x16_bf16 v[2:17], v[66:69], v[198:201], v[2:17]
	ds_read_b64_tr_b16 v[198:199], v180 offset:512
	ds_read_b64_tr_b16 v[200:201], v180 offset:2560
	v_add_f32_e32 v202, v239, v202
	v_exp_f32_e32 v239, v98
	v_lshl_add_u64 v[188:189], v[196:197], 0, s[48:49]
	v_lshl_add_u64 v[186:187], v[194:195], 0, s[48:49]
	s_waitcnt lgkmcnt(6)
	v_mfma_f32_32x32x16_bf16 v[2:17], v[70:73], v[226:229], v[2:17]
	ds_read_b64_tr_b16 v[226:227], v180 offset:4608
	ds_read_b64_tr_b16 v[228:229], v180 offset:6656
	v_add_f32_e32 v202, v240, v202
	v_exp_f32_e32 v240, v99
	v_add_co_u32_e32 v164, vcc, s62, v188
	s_mov_b32 s3, 0x5f238000
	s_waitcnt lgkmcnt(6)
	v_mfma_f32_32x32x16_bf16 v[2:17], v[74:77], v[230:233], v[2:17]
	ds_read_b64_tr_b16 v[230:231], v180 offset:8704
	ds_read_b64_tr_b16 v[232:233], v180 offset:10752
	v_add_f32_e32 v202, v241, v202
	v_exp_f32_e32 v241, v100
	v_addc_co_u32_e32 v165, vcc, 0, v189, vcc
	v_add_co_u32_e32 v168, vcc, s59, v188
	s_waitcnt lgkmcnt(6)
	v_mfma_f32_32x32x16_bf16 v[2:17], v[78:81], v[234:237], v[2:17]
	ds_read_b64_tr_b16 v[234:235], v180 offset:12800
	ds_read_b64_tr_b16 v[236:237], v180 offset:14848
	v_add_f32_e32 v202, v242, v202
	v_exp_f32_e32 v242, v101
	global_load_dwordx4 v[164:167], v[164:165], off offset:1024
	v_addc_co_u32_e32 v169, vcc, 0, v189, vcc
	v_add_co_u32_e32 v172, vcc, s24, v186
	s_waitcnt lgkmcnt(6)
	v_mfma_f32_32x32x16_bf16 v[18:33], v[66:69], v[198:201], v[18:33]
	ds_read_b64_tr_b16 v[198:199], v180 offset:1024
	ds_read_b64_tr_b16 v[200:201], v180 offset:3072
	v_add_f32_e32 v202, v243, v202
	v_exp_f32_e32 v243, v102
	global_load_dwordx4 v[168:171], v[168:169], off offset:1024
	v_addc_co_u32_e32 v173, vcc, 0, v187, vcc
	v_add_co_u32_e32 v176, vcc, s3, v186
	s_waitcnt lgkmcnt(6)
	v_mfma_f32_32x32x16_bf16 v[18:33], v[70:73], v[226:229], v[18:33]
	ds_read_b64_tr_b16 v[226:227], v180 offset:5120
	ds_read_b64_tr_b16 v[228:229], v180 offset:7168
	v_add_f32_e32 v202, v244, v202
	v_exp_f32_e32 v244, v103
	global_load_dwordx4 v[172:175], v[172:173], off
	v_addc_co_u32_e32 v177, vcc, 0, v187, vcc
	s_waitcnt lgkmcnt(6)
	v_mfma_f32_32x32x16_bf16 v[18:33], v[74:77], v[230:233], v[18:33]
	ds_read_b64_tr_b16 v[230:231], v180 offset:9216
	ds_read_b64_tr_b16 v[232:233], v180 offset:11264
	v_add_f32_e32 v202, v245, v202
	v_exp_f32_e32 v245, v104
	v_add_f32_e32 v202, v246, v202
	v_exp_f32_e32 v246, v105
	global_load_dwordx4 v[176:179], v[176:177], off
	s_waitcnt lgkmcnt(6)
	v_mfma_f32_32x32x16_bf16 v[18:33], v[78:81], v[234:237], v[18:33]
	ds_read_b64_tr_b16 v[234:235], v180 offset:13312
	ds_read_b64_tr_b16 v[236:237], v180 offset:15360
	v_add_f32_e32 v202, v247, v202
	v_exp_f32_e32 v247, v106
	v_add_f32_e32 v202, v248, v202
	v_exp_f32_e32 v248, v107
	s_waitcnt lgkmcnt(6)
	v_mfma_f32_32x32x16_bf16 v[34:49], v[66:69], v[198:201], v[34:49]
	ds_read_b64_tr_b16 v[198:199], v180 offset:1536
	ds_read_b64_tr_b16 v[200:201], v180 offset:3584
	v_add_f32_e32 v202, v249, v202
	v_exp_f32_e32 v249, v108
	v_add_f32_e32 v202, v250, v202
	v_exp_f32_e32 v250, v109
	s_waitcnt lgkmcnt(6)
	v_mfma_f32_32x32x16_bf16 v[34:49], v[70:73], v[226:229], v[34:49]
	ds_read_b64_tr_b16 v[226:227], v180 offset:5632
	ds_read_b64_tr_b16 v[228:229], v180 offset:7680
	v_add_f32_e32 v202, v251, v202
	v_exp_f32_e32 v251, v110
	v_add_f32_e32 v202, v252, v202
	v_exp_f32_e32 v252, v111
	s_waitcnt lgkmcnt(6)
	v_mfma_f32_32x32x16_bf16 v[34:49], v[74:77], v[230:233], v[34:49]
	ds_read_b64_tr_b16 v[230:231], v180 offset:9728
	ds_read_b64_tr_b16 v[232:233], v180 offset:11776
	v_add_f32_e32 v202, v182, v202
	v_exp_f32_e32 v182, v112
	v_add_f32_e32 v202, v183, v202
	v_exp_f32_e32 v183, v113
	s_waitcnt lgkmcnt(6)
	v_mfma_f32_32x32x16_bf16 v[34:49], v[78:81], v[234:237], v[34:49]
	ds_read_b64_tr_b16 v[234:235], v180 offset:13824
	ds_read_b64_tr_b16 v[236:237], v180 offset:15872
	v_mov_b32_e32 v238, v202
	s_waitcnt lgkmcnt(0)
	v_mfma_f32_32x32x16_bf16 v[50:65], v[66:69], v[198:201], v[50:65]
	s_barrier
	ds_write_b128 v217, v[148:151] offset:0
	ds_write_b128 v218, v[152:155] offset:0
	ds_read_b128 v[156:159], v221 offset:32768
	ds_read_b128 v[160:163], v221 offset:40960
	v_permlane32_swap_b32_e32 v202, v238
	v_mfma_f32_32x32x16_bf16 v[50:65], v[70:73], v[226:229], v[50:65]
	v_add_f32_e32 v238, v202, v238
	v_add_f32_e32 v1, v1, v238
	ds_read_b128 v[148:151], v223 offset:32768
	ds_read_b128 v[152:155], v223 offset:40960
	v_mfma_f32_32x32x16_bf16 v[50:65], v[74:77], v[230:233], v[50:65]
	v_mfma_f32_32x32x16_bf16 v[50:65], v[78:81], v[234:237], v[50:65]
	s_waitcnt lgkmcnt(3)
	v_mfma_f32_32x32x16_bf16 v[98:113], v[156:159], v[144:147], 0
	v_exp_f32_e32 v229, v82
	v_exp_f32_e32 v230, v83
	v_add_f32_e32 v202, 0, v239
	s_waitcnt lgkmcnt(2)
	v_mfma_f32_32x32x16_bf16 v[66:81], v[160:163], v[144:147], 0
	ds_read_b128 v[156:159], v219 offset:32768
	ds_read_b128 v[160:163], v219 offset:40960
	v_exp_f32_e32 v231, v84
	v_exp_f32_e32 v233, v85
	v_add_f32_e32 v202, v240, v202
	s_waitcnt lgkmcnt(3)
	v_mfma_f32_32x32x16_bf16 v[98:113], v[148:151], v[140:143], v[98:113]
	v_exp_f32_e32 v234, v86
	v_exp_f32_e32 v236, v87
	v_add_f32_e32 v202, v241, v202
	s_waitcnt lgkmcnt(2)
	v_mfma_f32_32x32x16_bf16 v[66:81], v[152:155], v[140:143], v[66:81]
	ds_read_b128 v[148:151], v216 offset:32768
	ds_read_b128 v[152:155], v216 offset:40960
	v_exp_f32_e32 v232, v88
	v_exp_f32_e32 v235, v89
	v_add_f32_e32 v202, v242, v202
	s_waitcnt lgkmcnt(3)
	v_mfma_f32_32x32x16_bf16 v[98:113], v[156:159], v[136:139], v[98:113]
	v_cvt_pk_bf16_f32 v82, v239, v240
	v_cvt_pk_bf16_f32 v83, v241, v242
	v_cvt_pk_bf16_f32 v84, v243, v244
	v_cvt_pk_bf16_f32 v85, v245, v246
	v_add_f32_e32 v202, v243, v202
	s_waitcnt lgkmcnt(2)
	v_mfma_f32_32x32x16_bf16 v[66:81], v[160:163], v[136:139], v[66:81]
	ds_read_b128 v[156:159], v215 offset:32768
	ds_read_b128 v[160:163], v215 offset:40960
	v_add_f32_e32 v202, v244, v202
	v_add_f32_e32 v202, v245, v202
	v_permlane32_swap_b32_e32 v82, v84
	v_permlane32_swap_b32_e32 v83, v85
	v_exp_f32_e32 v199, v90
	s_waitcnt lgkmcnt(3)
	v_mfma_f32_32x32x16_bf16 v[98:113], v[148:151], v[132:135], v[98:113]
	v_exp_f32_e32 v200, v91
	v_add_f32_e32 v202, v246, v202
	v_add_f32_e32 v202, v247, v202
	v_add_f32_e32 v202, v248, v202
	s_waitcnt lgkmcnt(2)
	v_mfma_f32_32x32x16_bf16 v[66:81], v[152:155], v[132:135], v[66:81]
	ds_read_b128 v[148:151], v214 offset:32768
	ds_read_b128 v[152:155], v214 offset:40960
	v_cvt_pk_bf16_f32 v86, v247, v248
	v_cvt_pk_bf16_f32 v87, v249, v250
	v_cvt_pk_bf16_f32 v88, v251, v252
	v_cvt_pk_bf16_f32 v89, v182, v183
	v_add_f32_e32 v202, v249, v202
	s_waitcnt lgkmcnt(3)
	v_mfma_f32_32x32x16_bf16 v[98:113], v[156:159], v[128:131], v[98:113]
	v_add_f32_e32 v202, v250, v202
	v_add_f32_e32 v202, v251, v202
	v_permlane32_swap_b32_e32 v86, v88
	v_permlane32_swap_b32_e32 v87, v89
	s_waitcnt vmcnt(0)
	ds_write_b128 v220, v[172:175] offset:49152
	ds_write_b128 v222, v[176:179] offset:49152
	s_waitcnt lgkmcnt(4)
	v_mfma_f32_32x32x16_bf16 v[66:81], v[160:163], v[128:131], v[66:81]
	ds_read_b128 v[156:159], v213 offset:32768
	ds_read_b128 v[160:163], v213 offset:40960
	v_exp_f32_e32 v201, v92
	v_exp_f32_e32 v227, v93
	v_add_f32_e32 v202, v252, v202
	s_waitcnt lgkmcnt(5)
	v_mfma_f32_32x32x16_bf16 v[98:113], v[148:151], v[124:127], v[98:113]
	v_exp_f32_e32 v198, v94
	v_exp_f32_e32 v225, v95
	v_add_f32_e32 v202, v182, v202
	s_waitcnt lgkmcnt(4)
	v_mfma_f32_32x32x16_bf16 v[66:81], v[152:155], v[124:127], v[66:81]
	ds_read_b128 v[148:151], v224 offset:32768
	ds_read_b128 v[152:155], v224 offset:40960
	v_exp_f32_e32 v226, v96
	v_exp_f32_e32 v228, v97
	v_add_f32_e32 v202, v183, v202
	s_waitcnt lgkmcnt(3)
	v_mfma_f32_32x32x16_bf16 v[98:113], v[156:159], v[120:123], v[98:113]
	v_cvt_pk_bf16_f32 v90, v229, v230
	v_cvt_pk_bf16_f32 v91, v231, v233
	v_cvt_pk_bf16_f32 v92, v234, v236
	v_cvt_pk_bf16_f32 v93, v232, v235
	s_waitcnt lgkmcnt(2)
	v_mfma_f32_32x32x16_bf16 v[66:81], v[160:163], v[120:123], v[66:81]
	v_cvt_pk_bf16_f32 v94, v199, v200
	v_cvt_pk_bf16_f32 v95, v201, v227
	v_permlane32_swap_b32_e32 v90, v92
	v_permlane32_swap_b32_e32 v91, v93
	ds_read_b64_tr_b16 v[240:241], v115 offset:0
	ds_read_b64_tr_b16 v[242:243], v115 offset:2048
	s_waitcnt lgkmcnt(3)
	v_mfma_f32_32x32x16_bf16 v[98:113], v[148:151], v[116:119], v[98:113]
	v_cvt_pk_bf16_f32 v96, v198, v225
	v_cvt_pk_bf16_f32 v97, v226, v228
	ds_read_b64_tr_b16 v[244:245], v115 offset:4096
	ds_read_b64_tr_b16 v[246:247], v115 offset:6144
	ds_read_b64_tr_b16 v[248:249], v115 offset:8192
	ds_read_b64_tr_b16 v[250:251], v115 offset:10240
	s_waitcnt lgkmcnt(6)
	v_mfma_f32_32x32x16_bf16 v[66:81], v[152:155], v[116:119], v[66:81]
	ds_read_b64_tr_b16 v[190:191], v115 offset:12288
	ds_read_b64_tr_b16 v[192:193], v115 offset:14336
	v_permlane32_swap_b32_e32 v94, v96
	v_permlane32_swap_b32_e32 v95, v97
	s_cmpk_gt_u32 s8, 0x7c
	s_cbranch_scc1 .Lattn_h2c_last
	s_waitcnt lgkmcnt(6)
	v_mfma_f32_32x32x16_bf16 v[2:17], v[82:85], v[240:243], v[2:17]
	ds_read_b64_tr_b16 v[240:241], v115 offset:512
	ds_read_b64_tr_b16 v[242:243], v115 offset:2560
	v_add_f32_e32 v202, v229, v202
	v_exp_f32_e32 v229, v98
	v_add_co_u32_e32 v148, vcc, 0x4d684000, v188
	s_waitcnt lgkmcnt(6)
	v_mfma_f32_32x32x16_bf16 v[2:17], v[86:89], v[244:247], v[2:17]
	ds_read_b64_tr_b16 v[244:245], v115 offset:4608
	ds_read_b64_tr_b16 v[246:247], v115 offset:6656
	v_add_f32_e32 v202, v230, v202
	v_exp_f32_e32 v230, v99
	v_addc_co_u32_e32 v149, vcc, 0, v189, vcc
	v_add_co_u32_e32 v152, vcc, 0x4d714000, v188
	s_waitcnt lgkmcnt(6)
	v_mfma_f32_32x32x16_bf16 v[2:17], v[90:93], v[248:251], v[2:17]
	ds_read_b64_tr_b16 v[248:249], v115 offset:8704
	ds_read_b64_tr_b16 v[250:251], v115 offset:10752
	v_add_f32_e32 v202, v231, v202
	v_exp_f32_e32 v231, v100
	global_load_dwordx4 v[148:151], v[148:149], off offset:1024
	v_addc_co_u32_e32 v153, vcc, 0, v189, vcc
	v_add_co_u32_e32 v156, vcc, 0x5f240000, v186
	s_waitcnt lgkmcnt(6)
	v_mfma_f32_32x32x16_bf16 v[2:17], v[94:97], v[190:193], v[2:17]
	ds_read_b64_tr_b16 v[190:191], v115 offset:12800
	ds_read_b64_tr_b16 v[192:193], v115 offset:14848
	v_add_f32_e32 v202, v233, v202
	v_exp_f32_e32 v233, v101
	global_load_dwordx4 v[152:155], v[152:153], off offset:1024
	v_addc_co_u32_e32 v157, vcc, 0, v187, vcc
	v_add_co_u32_e32 v160, vcc, 0x5f248000, v186
	s_waitcnt lgkmcnt(6)
	v_mfma_f32_32x32x16_bf16 v[18:33], v[82:85], v[240:243], v[18:33]
	ds_read_b64_tr_b16 v[240:241], v115 offset:1024
	ds_read_b64_tr_b16 v[242:243], v115 offset:3072
	v_add_f32_e32 v202, v234, v202
	v_exp_f32_e32 v234, v102
	global_load_dwordx4 v[156:159], v[156:157], off
	v_addc_co_u32_e32 v161, vcc, 0, v187, vcc
	s_waitcnt lgkmcnt(6)
	v_mfma_f32_32x32x16_bf16 v[18:33], v[86:89], v[244:247], v[18:33]
	ds_read_b64_tr_b16 v[244:245], v115 offset:5120
	ds_read_b64_tr_b16 v[246:247], v115 offset:7168
	v_add_f32_e32 v202, v236, v202
	v_exp_f32_e32 v236, v103
	global_load_dwordx4 v[160:163], v[160:161], off
	s_waitcnt lgkmcnt(6)
	v_mfma_f32_32x32x16_bf16 v[18:33], v[90:93], v[248:251], v[18:33]
	ds_read_b64_tr_b16 v[248:249], v115 offset:9216
	ds_read_b64_tr_b16 v[250:251], v115 offset:11264
	v_add_f32_e32 v202, v232, v202
	v_exp_f32_e32 v232, v104
	v_add_f32_e32 v202, v235, v202
	v_exp_f32_e32 v235, v105
	s_waitcnt lgkmcnt(6)
	v_mfma_f32_32x32x16_bf16 v[18:33], v[94:97], v[190:193], v[18:33]
	ds_read_b64_tr_b16 v[190:191], v115 offset:13312
	ds_read_b64_tr_b16 v[192:193], v115 offset:15360
	v_add_f32_e32 v202, v199, v202
	v_exp_f32_e32 v199, v106
	v_add_f32_e32 v202, v200, v202
	v_exp_f32_e32 v200, v107
	s_waitcnt lgkmcnt(6)
	v_mfma_f32_32x32x16_bf16 v[34:49], v[82:85], v[240:243], v[34:49]
	ds_read_b64_tr_b16 v[240:241], v115 offset:1536
	ds_read_b64_tr_b16 v[242:243], v115 offset:3584
	v_add_f32_e32 v202, v201, v202
	v_exp_f32_e32 v201, v108
	v_add_f32_e32 v202, v227, v202
	v_exp_f32_e32 v227, v109
	s_waitcnt lgkmcnt(6)
	v_mfma_f32_32x32x16_bf16 v[34:49], v[86:89], v[244:247], v[34:49]
	ds_read_b64_tr_b16 v[244:245], v115 offset:5632
	ds_read_b64_tr_b16 v[246:247], v115 offset:7680
	v_add_f32_e32 v202, v198, v202
	v_exp_f32_e32 v198, v110
	v_add_f32_e32 v202, v225, v202
	v_exp_f32_e32 v225, v111
	s_waitcnt lgkmcnt(6)
	v_mfma_f32_32x32x16_bf16 v[34:49], v[90:93], v[248:251], v[34:49]
	ds_read_b64_tr_b16 v[248:249], v115 offset:9728
	ds_read_b64_tr_b16 v[250:251], v115 offset:11776
	v_add_f32_e32 v202, v226, v202
	v_exp_f32_e32 v226, v112
	v_add_f32_e32 v202, v228, v202
	v_exp_f32_e32 v228, v113
	s_waitcnt lgkmcnt(6)
	v_mfma_f32_32x32x16_bf16 v[34:49], v[94:97], v[190:193], v[34:49]
	ds_read_b64_tr_b16 v[190:191], v115 offset:13824
	ds_read_b64_tr_b16 v[192:193], v115 offset:15872
	v_mov_b32_e32 v238, v202
	s_waitcnt lgkmcnt(0)
	v_mfma_f32_32x32x16_bf16 v[50:65], v[82:85], v[240:243], v[50:65]
	s_barrier
	ds_write_b128 v217, v[164:167] offset:16384
	ds_write_b128 v218, v[168:171] offset:16384
	ds_read_b128 v[172:175], v221 offset:49152
	ds_read_b128 v[176:179], v221 offset:57344
	v_permlane32_swap_b32_e32 v202, v238
	v_mfma_f32_32x32x16_bf16 v[50:65], v[86:89], v[244:247], v[50:65]
	v_add_f32_e32 v238, v202, v238
	v_add_f32_e32 v1, v1, v238
	ds_read_b128 v[164:167], v223 offset:49152
	ds_read_b128 v[168:171], v223 offset:57344
	v_mfma_f32_32x32x16_bf16 v[50:65], v[90:93], v[248:251], v[50:65]
	v_mfma_f32_32x32x16_bf16 v[50:65], v[94:97], v[190:193], v[50:65]
	v_lshl_add_u64 v[194:195], v[194:195], 0, s[30:31]
	v_lshl_add_u64 v[196:197], v[196:197], 0, s[80:81]
	s_add_i32 s8, s8, 2
	s_branch .Lattn_h1
.Lattn_h2c_last:
	s_waitcnt lgkmcnt(6)
	v_mfma_f32_32x32x16_bf16 v[2:17], v[82:85], v[240:243], v[2:17]
	ds_read_b64_tr_b16 v[240:241], v115 offset:512
	ds_read_b64_tr_b16 v[242:243], v115 offset:2560
	v_add_f32_e32 v202, v229, v202
	v_exp_f32_e32 v229, v98
	s_waitcnt lgkmcnt(6)
	v_mfma_f32_32x32x16_bf16 v[2:17], v[86:89], v[244:247], v[2:17]
	ds_read_b64_tr_b16 v[244:245], v115 offset:4608
	ds_read_b64_tr_b16 v[246:247], v115 offset:6656
	v_add_f32_e32 v202, v230, v202
	v_exp_f32_e32 v230, v99
	s_waitcnt lgkmcnt(6)
	v_mfma_f32_32x32x16_bf16 v[2:17], v[90:93], v[248:251], v[2:17]
	ds_read_b64_tr_b16 v[248:249], v115 offset:8704
	ds_read_b64_tr_b16 v[250:251], v115 offset:10752
	v_add_f32_e32 v202, v231, v202
	v_exp_f32_e32 v231, v100
	s_waitcnt lgkmcnt(6)
	v_mfma_f32_32x32x16_bf16 v[2:17], v[94:97], v[190:193], v[2:17]
	ds_read_b64_tr_b16 v[190:191], v115 offset:12800
	ds_read_b64_tr_b16 v[192:193], v115 offset:14848
	v_add_f32_e32 v202, v233, v202
	v_exp_f32_e32 v233, v101
	s_waitcnt lgkmcnt(6)
	v_mfma_f32_32x32x16_bf16 v[18:33], v[82:85], v[240:243], v[18:33]
	ds_read_b64_tr_b16 v[240:241], v115 offset:1024
	ds_read_b64_tr_b16 v[242:243], v115 offset:3072
	v_add_f32_e32 v202, v234, v202
	v_exp_f32_e32 v234, v102
	s_waitcnt lgkmcnt(6)
	v_mfma_f32_32x32x16_bf16 v[18:33], v[86:89], v[244:247], v[18:33]
	ds_read_b64_tr_b16 v[244:245], v115 offset:5120
	ds_read_b64_tr_b16 v[246:247], v115 offset:7168
	v_add_f32_e32 v202, v236, v202
	v_exp_f32_e32 v236, v103
	s_waitcnt lgkmcnt(6)
	v_mfma_f32_32x32x16_bf16 v[18:33], v[90:93], v[248:251], v[18:33]
	ds_read_b64_tr_b16 v[248:249], v115 offset:9216
	ds_read_b64_tr_b16 v[250:251], v115 offset:11264
	v_add_f32_e32 v202, v232, v202
	v_exp_f32_e32 v232, v104
	v_add_f32_e32 v202, v235, v202
	v_exp_f32_e32 v235, v105
	s_waitcnt lgkmcnt(6)
	v_mfma_f32_32x32x16_bf16 v[18:33], v[94:97], v[190:193], v[18:33]
	ds_read_b64_tr_b16 v[190:191], v115 offset:13312
	ds_read_b64_tr_b16 v[192:193], v115 offset:15360
	v_add_f32_e32 v202, v199, v202
	v_exp_f32_e32 v199, v106
	v_add_f32_e32 v202, v200, v202
	v_exp_f32_e32 v200, v107
	s_waitcnt lgkmcnt(6)
	v_mfma_f32_32x32x16_bf16 v[34:49], v[82:85], v[240:243], v[34:49]
	ds_read_b64_tr_b16 v[240:241], v115 offset:1536
	ds_read_b64_tr_b16 v[242:243], v115 offset:3584
	v_add_f32_e32 v202, v201, v202
	v_exp_f32_e32 v201, v108
	v_add_f32_e32 v202, v227, v202
	v_exp_f32_e32 v227, v109
	s_waitcnt lgkmcnt(6)
	v_mfma_f32_32x32x16_bf16 v[34:49], v[86:89], v[244:247], v[34:49]
	ds_read_b64_tr_b16 v[244:245], v115 offset:5632
	ds_read_b64_tr_b16 v[246:247], v115 offset:7680
	v_add_f32_e32 v202, v198, v202
	v_exp_f32_e32 v198, v110
	v_add_f32_e32 v202, v225, v202
	v_exp_f32_e32 v225, v111
	s_waitcnt lgkmcnt(6)
	v_mfma_f32_32x32x16_bf16 v[34:49], v[90:93], v[248:251], v[34:49]
	ds_read_b64_tr_b16 v[248:249], v115 offset:9728
	ds_read_b64_tr_b16 v[250:251], v115 offset:11776
	v_add_f32_e32 v202, v226, v202
	v_exp_f32_e32 v226, v112
	v_add_f32_e32 v202, v228, v202
	v_exp_f32_e32 v228, v113
	s_waitcnt lgkmcnt(6)
	v_mfma_f32_32x32x16_bf16 v[34:49], v[94:97], v[190:193], v[34:49]
	ds_read_b64_tr_b16 v[190:191], v115 offset:13824
	ds_read_b64_tr_b16 v[192:193], v115 offset:15872
	v_mov_b32_e32 v238, v202
	s_waitcnt lgkmcnt(0)
	v_mfma_f32_32x32x16_bf16 v[50:65], v[82:85], v[240:243], v[50:65]
	s_barrier
	ds_write_b128 v217, v[164:167] offset:16384
	ds_write_b128 v218, v[168:171] offset:16384
	v_permlane32_swap_b32_e32 v202, v238
	v_mfma_f32_32x32x16_bf16 v[50:65], v[86:89], v[244:247], v[50:65]
	v_add_f32_e32 v238, v202, v238
	v_add_f32_e32 v1, v1, v238
	v_mfma_f32_32x32x16_bf16 v[50:65], v[90:93], v[248:251], v[50:65]
	v_mfma_f32_32x32x16_bf16 v[50:65], v[94:97], v[190:193], v[50:65]
	v_mov_b64_e32 v[186:187], 0x400
	v_mov_b64_e32 v[188:189], 0x3ff
	v_mov_b64_e32 v[190:191], 0x1000
	v_mov_b64_e32 v[192:193], 0xfff
